# GEMM main loop: the four mid-segment s_setprio 0/1 flip pairs removed (each 32-MFMA segment runs at one raised priority), on top of v86
# baseline (speedup 1.0000x reference)
.LBB0_2002:
	s_add_i32 s72, s51, 2
	s_add_u32 s24, s2, 0x80
	s_addc_u32 s25, s3, 0
	s_add_i32 s73, 0, 0x10000
	s_cmp_eq_u32 s31, s51
	s_cselect_b32 s25, s45, s25
	s_cselect_b32 s24, s44, s24
	s_cselect_b32 vcc_hi, s39, s71
	s_cselect_b32 vcc_lo, s38, s11
	s_add_i32 s51, 0, 0x14000
	v_add_u32_e32 v154, s73, v162
	v_add_u32_e32 v180, s51, v162
	ds_read_b128 v[130:133], v154
	ds_read_b128 v[134:137], v154 offset:1024
	ds_read_b128 v[150:153], v154 offset:2048
	ds_read_b128 v[154:157], v154 offset:3072
	ds_read_b128 v[168:171], v180
	ds_read_b128 v[172:175], v180 offset:1024
	ds_read_b128 v[176:179], v180 offset:2048
	ds_read_b128 v[180:183], v180 offset:3072
	v_lshl_add_u64 v[200:201], s[2:3], 0, v[148:149]
	s_add_i32 m0, s61, 0xc000
	ds_read_b128 v[184:187], v167
	ds_read_b128 v[188:191], v167 offset:1024
	ds_read_b128 v[192:195], v167 offset:2048
	ds_read_b128 v[196:199], v167 offset:3072
	ds_read_b128 v[220:223], v167 offset:4096
	ds_read_b128 v[224:227], v167 offset:5120
	ds_read_b128 v[228:231], v167 offset:6144
	ds_read_b128 v[232:235], v167 offset:7168
	global_load_lds_dwordx4 v[200:201], off
	v_lshl_add_u64 v[200:201], s[2:3], 0, v[146:147]
	s_add_i32 m0, s61, 0xe000
	s_nop 0
	global_load_lds_dwordx4 v[200:201], off
	s_waitcnt vmcnt(8)
	s_waitcnt lgkmcnt(0)
	s_barrier
	s_setprio 1
	s_waitcnt lgkmcnt(0)
	v_mfma_f32_16x16x32_bf16 v[122:125], v[130:133], v[184:187], v[122:125]
	v_mfma_f32_16x16x32_bf16 v[118:121], v[150:153], v[184:187], v[118:121]
	v_mfma_f32_16x16x32_bf16 v[102:105], v[130:133], v[192:195], v[102:105]
	v_mfma_f32_16x16x32_bf16 v[98:101], v[150:153], v[192:195], v[98:101]
	v_mfma_f32_16x16x32_bf16 v[86:89], v[130:133], v[220:223], v[86:89]
	v_mfma_f32_16x16x32_bf16 v[82:85], v[150:153], v[220:223], v[82:85]
	v_mfma_f32_16x16x32_bf16 v[70:73], v[130:133], v[228:231], v[70:73]
	v_mfma_f32_16x16x32_bf16 v[66:69], v[150:153], v[228:231], v[66:69]
	v_mfma_f32_16x16x32_bf16 v[122:125], v[134:137], v[188:191], v[122:125]
	v_mfma_f32_16x16x32_bf16 v[118:121], v[154:157], v[188:191], v[118:121]
	v_mfma_f32_16x16x32_bf16 v[102:105], v[134:137], v[196:199], v[102:105]
	v_mfma_f32_16x16x32_bf16 v[98:101], v[154:157], v[196:199], v[98:101]
	v_mfma_f32_16x16x32_bf16 v[86:89], v[134:137], v[224:227], v[86:89]
	v_mfma_f32_16x16x32_bf16 v[82:85], v[154:157], v[224:227], v[82:85]
	v_mfma_f32_16x16x32_bf16 v[70:73], v[134:137], v[232:235], v[70:73]
	v_mfma_f32_16x16x32_bf16 v[66:69], v[154:157], v[232:235], v[66:69]
	v_mfma_f32_16x16x32_bf16 v[114:117], v[168:171], v[184:187], v[114:117]
	v_mfma_f32_16x16x32_bf16 v[126:129], v[176:179], v[184:187], v[126:129]
	v_mfma_f32_16x16x32_bf16 v[110:113], v[168:171], v[192:195], v[110:113]
	v_mfma_f32_16x16x32_bf16 v[106:109], v[176:179], v[192:195], v[106:109]
	v_mfma_f32_16x16x32_bf16 v[94:97], v[168:171], v[220:223], v[94:97]
	v_mfma_f32_16x16x32_bf16 v[90:93], v[176:179], v[220:223], v[90:93]
	v_mfma_f32_16x16x32_bf16 v[78:81], v[168:171], v[228:231], v[78:81]
	v_mfma_f32_16x16x32_bf16 v[74:77], v[176:179], v[228:231], v[74:77]
	v_mfma_f32_16x16x32_bf16 v[114:117], v[172:175], v[188:191], v[114:117]
	v_mfma_f32_16x16x32_bf16 v[126:129], v[180:183], v[188:191], v[126:129]
	v_mfma_f32_16x16x32_bf16 v[110:113], v[172:175], v[196:199], v[110:113]
	v_mfma_f32_16x16x32_bf16 v[106:109], v[180:183], v[196:199], v[106:109]
	v_mfma_f32_16x16x32_bf16 v[94:97], v[172:175], v[224:227], v[94:97]
	v_mfma_f32_16x16x32_bf16 v[90:93], v[180:183], v[224:227], v[90:93]
	v_mfma_f32_16x16x32_bf16 v[78:81], v[172:175], v[232:235], v[78:81]
	v_mfma_f32_16x16x32_bf16 v[74:77], v[180:183], v[232:235], v[74:77]
	s_setprio 0
	s_barrier
	s_add_i32 s73, s73, s75
	v_lshl_add_u64 v[200:201], vcc, 0, v[0:1]
	s_mov_b32 m0, s73
	ds_read_b128 v[184:187], v167 offset:16384
	ds_read_b128 v[188:191], v167 offset:17408
	ds_read_b128 v[192:195], v167 offset:18432
	ds_read_b128 v[196:199], v167 offset:19456
	ds_read_b128 v[220:223], v167 offset:20480
	ds_read_b128 v[224:227], v167 offset:21504
	ds_read_b128 v[228:231], v167 offset:22528
	ds_read_b128 v[232:235], v167 offset:23552
	global_load_lds_dwordx4 v[200:201], off
	s_add_i32 m0, s73, 0x2000
	v_lshl_add_u64 v[236:237], vcc, 0, v[144:145]
	s_add_u32 vcc_lo, vcc_lo, s46
	s_addc_u32 vcc_hi, vcc_hi, 0
	s_add_i32 s51, s51, s75
	global_load_lds_dwordx4 v[236:237], off
	v_lshl_add_u64 v[238:239], vcc, 0, v[0:1]
	s_mov_b32 m0, s51
	v_lshl_add_u64 v[240:241], vcc, 0, v[144:145]
	global_load_lds_dwordx4 v[238:239], off
	s_add_i32 m0, s51, 0x2000
	v_lshl_add_u64 v[242:243], s[24:25], 0, v[140:141]
	global_load_lds_dwordx4 v[240:241], off
	s_mov_b32 m0, s61
	v_lshl_add_u64 v[244:245], s[24:25], 0, v[142:143]
	global_load_lds_dwordx4 v[242:243], off
	s_mov_b32 m0, s76
	s_nop 0
	global_load_lds_dwordx4 v[244:245], off
	s_waitcnt vmcnt(8)
	s_waitcnt lgkmcnt(0)
	s_barrier
	s_setprio 1
	s_waitcnt lgkmcnt(0)
	v_mfma_f32_16x16x32_bf16 v[54:57], v[130:133], v[184:187], v[54:57]
	v_mfma_f32_16x16x32_bf16 v[50:53], v[150:153], v[184:187], v[50:53]
	v_mfma_f32_16x16x32_bf16 v[42:45], v[130:133], v[192:195], v[42:45]
	v_mfma_f32_16x16x32_bf16 v[38:41], v[150:153], v[192:195], v[38:41]
	v_mfma_f32_16x16x32_bf16 v[30:33], v[130:133], v[220:223], v[30:33]
	v_mfma_f32_16x16x32_bf16 v[26:29], v[150:153], v[220:223], v[26:29]
	v_mfma_f32_16x16x32_bf16 v[14:17], v[130:133], v[228:231], v[14:17]
	v_mfma_f32_16x16x32_bf16 v[10:13], v[150:153], v[228:231], v[10:13]
	v_mfma_f32_16x16x32_bf16 v[54:57], v[134:137], v[188:191], v[54:57]
	v_mfma_f32_16x16x32_bf16 v[50:53], v[154:157], v[188:191], v[50:53]
	v_mfma_f32_16x16x32_bf16 v[42:45], v[134:137], v[196:199], v[42:45]
	v_mfma_f32_16x16x32_bf16 v[38:41], v[154:157], v[196:199], v[38:41]
	v_mfma_f32_16x16x32_bf16 v[30:33], v[134:137], v[224:227], v[30:33]
	v_mfma_f32_16x16x32_bf16 v[26:29], v[154:157], v[224:227], v[26:29]
	v_mfma_f32_16x16x32_bf16 v[14:17], v[134:137], v[232:235], v[14:17]
	v_mfma_f32_16x16x32_bf16 v[10:13], v[154:157], v[232:235], v[10:13]
	v_mfma_f32_16x16x32_bf16 v[62:65], v[168:171], v[184:187], v[62:65]
	v_mfma_f32_16x16x32_bf16 v[58:61], v[176:179], v[184:187], v[58:61]
	v_mfma_f32_16x16x32_bf16 v[46:49], v[168:171], v[192:195], v[46:49]
	v_mfma_f32_16x16x32_bf16 v[34:37], v[176:179], v[192:195], v[34:37]
	v_mfma_f32_16x16x32_bf16 v[22:25], v[168:171], v[220:223], v[22:25]
	v_mfma_f32_16x16x32_bf16 v[18:21], v[176:179], v[220:223], v[18:21]
	v_mfma_f32_16x16x32_bf16 v[6:9], v[168:171], v[228:231], v[6:9]
	v_mfma_f32_16x16x32_bf16 v[2:5], v[176:179], v[228:231], v[2:5]
	v_mfma_f32_16x16x32_bf16 v[62:65], v[172:175], v[188:191], v[62:65]
	v_mfma_f32_16x16x32_bf16 v[58:61], v[180:183], v[188:191], v[58:61]
	v_mfma_f32_16x16x32_bf16 v[46:49], v[172:175], v[196:199], v[46:49]
	v_mfma_f32_16x16x32_bf16 v[34:37], v[180:183], v[196:199], v[34:37]
	v_mfma_f32_16x16x32_bf16 v[22:25], v[172:175], v[224:227], v[22:25]
	v_mfma_f32_16x16x32_bf16 v[18:21], v[180:183], v[224:227], v[18:21]
	v_mfma_f32_16x16x32_bf16 v[6:9], v[172:175], v[232:235], v[6:9]
	v_mfma_f32_16x16x32_bf16 v[2:5], v[180:183], v[232:235], v[2:5]
	s_setprio 0
	s_barrier
	s_add_i32 s51, 0, 0x18000
	s_add_i32 s73, 0, 0x1c000
	v_add_u32_e32 v154, s51, v162
	v_add_u32_e32 v180, s73, v162
	ds_read_b128 v[130:133], v154
	ds_read_b128 v[134:137], v154 offset:1024
	ds_read_b128 v[150:153], v154 offset:2048
	ds_read_b128 v[154:157], v154 offset:3072
	ds_read_b128 v[168:171], v180
	ds_read_b128 v[172:175], v180 offset:1024
	ds_read_b128 v[176:179], v180 offset:2048
	ds_read_b128 v[180:183], v180 offset:3072
	s_add_u32 s24, s24, s46
	s_addc_u32 s25, s25, 0
	s_mov_b32 m0, s77
	v_lshl_add_u64 v[246:247], s[24:25], 0, v[140:141]
	ds_read_b128 v[184:187], v167 offset:32768
	ds_read_b128 v[188:191], v167 offset:33792
	ds_read_b128 v[192:195], v167 offset:34816
	ds_read_b128 v[196:199], v167 offset:35840
	ds_read_b128 v[220:223], v167 offset:36864
	ds_read_b128 v[224:227], v167 offset:37888
	ds_read_b128 v[228:231], v167 offset:38912
	ds_read_b128 v[232:235], v167 offset:39936
	global_load_lds_dwordx4 v[246:247], off
	v_lshl_add_u64 v[246:247], s[24:25], 0, v[142:143]
	s_mov_b32 m0, s28
	s_nop 0
	global_load_lds_dwordx4 v[246:247], off
	s_waitcnt vmcnt(8)
	s_waitcnt lgkmcnt(0)
	s_barrier
	s_setprio 1
	s_waitcnt lgkmcnt(0)
	v_mfma_f32_16x16x32_bf16 v[122:125], v[130:133], v[184:187], v[122:125]
	v_mfma_f32_16x16x32_bf16 v[118:121], v[150:153], v[184:187], v[118:121]
	v_mfma_f32_16x16x32_bf16 v[102:105], v[130:133], v[192:195], v[102:105]
	v_mfma_f32_16x16x32_bf16 v[98:101], v[150:153], v[192:195], v[98:101]
	v_mfma_f32_16x16x32_bf16 v[86:89], v[130:133], v[220:223], v[86:89]
	v_mfma_f32_16x16x32_bf16 v[82:85], v[150:153], v[220:223], v[82:85]
	v_mfma_f32_16x16x32_bf16 v[70:73], v[130:133], v[228:231], v[70:73]
	v_mfma_f32_16x16x32_bf16 v[66:69], v[150:153], v[228:231], v[66:69]
	v_mfma_f32_16x16x32_bf16 v[122:125], v[134:137], v[188:191], v[122:125]
	v_mfma_f32_16x16x32_bf16 v[118:121], v[154:157], v[188:191], v[118:121]
	v_mfma_f32_16x16x32_bf16 v[102:105], v[134:137], v[196:199], v[102:105]
	v_mfma_f32_16x16x32_bf16 v[98:101], v[154:157], v[196:199], v[98:101]
	v_mfma_f32_16x16x32_bf16 v[86:89], v[134:137], v[224:227], v[86:89]
	v_mfma_f32_16x16x32_bf16 v[82:85], v[154:157], v[224:227], v[82:85]
	v_mfma_f32_16x16x32_bf16 v[70:73], v[134:137], v[232:235], v[70:73]
	v_mfma_f32_16x16x32_bf16 v[66:69], v[154:157], v[232:235], v[66:69]
	v_mfma_f32_16x16x32_bf16 v[114:117], v[168:171], v[184:187], v[114:117]
	v_mfma_f32_16x16x32_bf16 v[126:129], v[176:179], v[184:187], v[126:129]
	v_mfma_f32_16x16x32_bf16 v[110:113], v[168:171], v[192:195], v[110:113]
	v_mfma_f32_16x16x32_bf16 v[106:109], v[176:179], v[192:195], v[106:109]
	v_mfma_f32_16x16x32_bf16 v[94:97], v[168:171], v[220:223], v[94:97]
	v_mfma_f32_16x16x32_bf16 v[90:93], v[176:179], v[220:223], v[90:93]
	v_mfma_f32_16x16x32_bf16 v[78:81], v[168:171], v[228:231], v[78:81]
	v_mfma_f32_16x16x32_bf16 v[74:77], v[176:179], v[228:231], v[74:77]
	v_mfma_f32_16x16x32_bf16 v[114:117], v[172:175], v[188:191], v[114:117]
	v_mfma_f32_16x16x32_bf16 v[126:129], v[180:183], v[188:191], v[126:129]
	v_mfma_f32_16x16x32_bf16 v[110:113], v[172:175], v[196:199], v[110:113]
	v_mfma_f32_16x16x32_bf16 v[106:109], v[180:183], v[196:199], v[106:109]
	v_mfma_f32_16x16x32_bf16 v[94:97], v[172:175], v[224:227], v[94:97]
	v_mfma_f32_16x16x32_bf16 v[90:93], v[180:183], v[224:227], v[90:93]
	v_mfma_f32_16x16x32_bf16 v[78:81], v[172:175], v[232:235], v[78:81]
	v_mfma_f32_16x16x32_bf16 v[74:77], v[180:183], v[232:235], v[74:77]
	s_setprio 0
	s_barrier
	s_add_i32 s24, s51, s75
	v_lshl_add_u64 v[200:201], v[200:201], 0, s[64:65]
	s_mov_b32 m0, s24
	ds_read_b128 v[184:187], v167 offset:49152
	ds_read_b128 v[188:191], v167 offset:50176
	ds_read_b128 v[192:195], v167 offset:51200
	ds_read_b128 v[196:199], v167 offset:52224
	ds_read_b128 v[220:223], v167 offset:53248
	ds_read_b128 v[224:227], v167 offset:54272
	ds_read_b128 v[228:231], v167 offset:55296
	ds_read_b128 v[232:235], v167 offset:56320
	global_load_lds_dwordx4 v[200:201], off
	v_lshl_add_u64 v[200:201], v[236:237], 0, s[64:65]
	s_add_i32 m0, s24, 0x2000
	s_add_i32 s24, s73, s75
	global_load_lds_dwordx4 v[200:201], off
	v_lshl_add_u64 v[200:201], v[238:239], 0, s[64:65]
	s_mov_b32 m0, s24
	s_nop 0
	global_load_lds_dwordx4 v[200:201], off
	v_lshl_add_u64 v[200:201], v[240:241], 0, s[64:65]
	s_add_i32 m0, s24, 0x2000
	s_nop 0
	global_load_lds_dwordx4 v[200:201], off
	v_lshl_add_u64 v[200:201], v[242:243], 0, s[64:65]
	s_mov_b32 m0, s29
	s_nop 0
	global_load_lds_dwordx4 v[200:201], off
	v_lshl_add_u64 v[200:201], v[244:245], 0, s[64:65]
	s_mov_b32 m0, s19
	s_nop 0
	global_load_lds_dwordx4 v[200:201], off
	s_waitcnt vmcnt(8)
	s_waitcnt lgkmcnt(0)
	s_barrier
	s_setprio 1
	s_waitcnt lgkmcnt(0)
	v_mfma_f32_16x16x32_bf16 v[54:57], v[130:133], v[184:187], v[54:57]
	v_mfma_f32_16x16x32_bf16 v[50:53], v[150:153], v[184:187], v[50:53]
	v_mfma_f32_16x16x32_bf16 v[42:45], v[130:133], v[192:195], v[42:45]
	v_mfma_f32_16x16x32_bf16 v[38:41], v[150:153], v[192:195], v[38:41]
	v_mfma_f32_16x16x32_bf16 v[30:33], v[130:133], v[220:223], v[30:33]
	v_mfma_f32_16x16x32_bf16 v[26:29], v[150:153], v[220:223], v[26:29]
	v_mfma_f32_16x16x32_bf16 v[14:17], v[130:133], v[228:231], v[14:17]
	v_mfma_f32_16x16x32_bf16 v[10:13], v[150:153], v[228:231], v[10:13]
	v_mfma_f32_16x16x32_bf16 v[54:57], v[134:137], v[188:191], v[54:57]
	v_mfma_f32_16x16x32_bf16 v[50:53], v[154:157], v[188:191], v[50:53]
	v_mfma_f32_16x16x32_bf16 v[42:45], v[134:137], v[196:199], v[42:45]
	v_mfma_f32_16x16x32_bf16 v[38:41], v[154:157], v[196:199], v[38:41]
	v_mfma_f32_16x16x32_bf16 v[30:33], v[134:137], v[224:227], v[30:33]
	v_mfma_f32_16x16x32_bf16 v[26:29], v[154:157], v[224:227], v[26:29]
	v_mfma_f32_16x16x32_bf16 v[14:17], v[134:137], v[232:235], v[14:17]
	v_mfma_f32_16x16x32_bf16 v[10:13], v[154:157], v[232:235], v[10:13]
	v_mfma_f32_16x16x32_bf16 v[62:65], v[168:171], v[184:187], v[62:65]
	v_mfma_f32_16x16x32_bf16 v[58:61], v[176:179], v[184:187], v[58:61]
	v_mfma_f32_16x16x32_bf16 v[46:49], v[168:171], v[192:195], v[46:49]
	v_mfma_f32_16x16x32_bf16 v[34:37], v[176:179], v[192:195], v[34:37]
	v_mfma_f32_16x16x32_bf16 v[22:25], v[168:171], v[220:223], v[22:25]
	v_mfma_f32_16x16x32_bf16 v[18:21], v[176:179], v[220:223], v[18:21]
	v_mfma_f32_16x16x32_bf16 v[6:9], v[168:171], v[228:231], v[6:9]
	v_mfma_f32_16x16x32_bf16 v[2:5], v[176:179], v[228:231], v[2:5]
	v_mfma_f32_16x16x32_bf16 v[62:65], v[172:175], v[188:191], v[62:65]
	v_mfma_f32_16x16x32_bf16 v[58:61], v[180:183], v[188:191], v[58:61]
	v_mfma_f32_16x16x32_bf16 v[46:49], v[172:175], v[196:199], v[46:49]
	v_mfma_f32_16x16x32_bf16 v[34:37], v[180:183], v[196:199], v[34:37]
	v_mfma_f32_16x16x32_bf16 v[22:25], v[172:175], v[224:227], v[22:25]
	v_mfma_f32_16x16x32_bf16 v[18:21], v[180:183], v[224:227], v[18:21]
	v_mfma_f32_16x16x32_bf16 v[6:9], v[172:175], v[232:235], v[6:9]
	v_mfma_f32_16x16x32_bf16 v[2:5], v[180:183], v[232:235], v[2:5]
	s_setprio 0
	s_barrier
	s_add_u32 s11, s11, 0x100
	s_addc_u32 s71, s71, 0
	s_add_u32 s2, s2, 0x100
	s_addc_u32 s3, s3, 0
	s_cmp_ge_u32 s72, s78
	s_mov_b32 s51, s72
	s_cbranch_scc0 .LBB0_2002
	s_and_b64 vcc, exec, s[68:69]
	s_cbranch_vccz .LBB0_2005
